# attention-B: V fragment LDS reads issued under the QK MFMAs instead of in front of them; tile-2 tsp and last K read issued before the mid-step staging
# baseline (speedup 1.0000x reference)
.LBB0_584:
	s_and_b32 s97, s22, 1
	s_mul_i32 s16, s97, 0x4800
	s_add_i32 s66, s16, 0
	s_cmp_lt_i32 s41, s37
	s_cselect_b64 s[16:17], -1, 0
	s_cmp_gt_i32 s41, s36
	s_cselect_b64 s[64:65], -1, 0
	s_or_b64 s[16:17], s[16:17], s[64:65]
	v_lshlrev_b32_e32 v0, 1, v190
	v_add_u32_e32 v2, s66, v244
	s_and_b64 vcc, exec, s[16:17]
	v_add3_u32 v234, s66, v243, v0
	v_add3_u32 v238, v2, v249, v250
	s_cbranch_vccnz .LBB0_598
	ds_read2_b64 v[180:183], v252 offset1:32
	ds_read_b128 v[172:175], v234
	ds_read_b128 v[160:163], v234 offset:32
	ds_read_b128 v[176:179], v234 offset:4608
	ds_read_b128 v[164:167], v234 offset:4640
	ds_read_b128 v[156:159], v234 offset:64
	ds_read_b128 v[152:155], v234 offset:96
	ds_read_b128 v[168:171], v234 offset:4672
	ds_read_b128 v[148:151], v234 offset:4704
	s_mov_b64 s[16:17], -1
	s_and_b64 vcc, exec, s[8:9]
	s_cbranch_vccz .LBB0_591
	s_add_i32 s16, s40, s63
	s_sub_i32 s16, s16, 63
	s_cmpk_gt_i32 s16, 0x7f
	s_mov_b64 s[16:17], -1
	s_cbranch_scc1 .LBB0_588
	v_add_u32_e32 v0, s40, v253
	v_add_u32_e32 v2, 0x5b, v0
	v_med3_i32 v3, v2, s53, v235
	v_med3_i32 v2, v2, s95, v237
	v_add_u32_e32 v4, 0x5a, v0
	v_add_u32_e32 v6, 0x59, v0
	v_add_u32_e32 v8, 0x58, v0
	v_lshl_add_u32 v3, v3, 2, s38
	v_lshl_add_u32 v2, v2, 2, s38
	v_med3_i32 v5, v4, s53, v235
	v_med3_i32 v4, v4, s95, v237
	v_med3_i32 v7, v6, s53, v235
	v_med3_i32 v6, v6, s95, v237
	v_med3_i32 v9, v8, s53, v235
	v_med3_i32 v8, v8, s95, v237
	v_lshl_add_u32 v5, v5, 2, s38
	v_lshl_add_u32 v4, v4, 2, s38
	v_lshl_add_u32 v7, v7, 2, s38
	v_lshl_add_u32 v6, v6, 2, s38
	v_lshl_add_u32 v9, v9, 2, s38
	v_lshl_add_u32 v8, v8, 2, s38
	ds_read_b32 v64, v3 offset:512
	ds_read_b32 v48, v2 offset:384
	ds_read_b32 v65, v5 offset:512
	ds_read_b32 v49, v4 offset:384
	ds_read_b32 v66, v7 offset:512
	ds_read_b32 v50, v6 offset:384
	ds_read_b32 v67, v9 offset:512
	ds_read_b32 v51, v8 offset:384
	v_add_u32_e32 v2, 0x53, v0
	v_med3_i32 v3, v2, s53, v235
	v_med3_i32 v2, v2, s95, v237
	v_add_u32_e32 v4, 0x52, v0
	v_add_u32_e32 v6, 0x51, v0
	v_add_u32_e32 v8, 0x50, v0
	v_lshl_add_u32 v3, v3, 2, s38
	v_lshl_add_u32 v2, v2, 2, s38
	v_med3_i32 v5, v4, s53, v235
	v_med3_i32 v4, v4, s95, v237
	v_med3_i32 v7, v6, s53, v235
	v_med3_i32 v6, v6, s95, v237
	v_med3_i32 v9, v8, s53, v235
	v_med3_i32 v8, v8, s95, v237
	v_lshl_add_u32 v5, v5, 2, s38
	v_lshl_add_u32 v4, v4, 2, s38
	v_lshl_add_u32 v7, v7, 2, s38
	v_lshl_add_u32 v6, v6, 2, s38
	v_lshl_add_u32 v9, v9, 2, s38
	v_lshl_add_u32 v8, v8, 2, s38
	ds_read_b32 v68, v3 offset:512
	ds_read_b32 v52, v2 offset:384
	ds_read_b32 v69, v5 offset:512
	ds_read_b32 v53, v4 offset:384
	ds_read_b32 v70, v7 offset:512
	ds_read_b32 v54, v6 offset:384
	ds_read_b32 v71, v9 offset:512
	ds_read_b32 v55, v8 offset:384
	v_add_u32_e32 v2, 0x4b, v0
	v_med3_i32 v3, v2, s53, v235
	v_med3_i32 v2, v2, s95, v237
	v_add_u32_e32 v4, 0x4a, v0
	v_add_u32_e32 v6, 0x49, v0
	v_add_u32_e32 v8, 0x48, v0
	v_lshl_add_u32 v3, v3, 2, s38
	v_lshl_add_u32 v2, v2, 2, s38
	v_med3_i32 v5, v4, s53, v235
	v_med3_i32 v4, v4, s95, v237
	v_med3_i32 v7, v6, s53, v235
	v_med3_i32 v6, v6, s95, v237
	v_med3_i32 v9, v8, s53, v235
	v_med3_i32 v8, v8, s95, v237
	v_lshl_add_u32 v5, v5, 2, s38
	v_lshl_add_u32 v4, v4, 2, s38
	v_lshl_add_u32 v7, v7, 2, s38
	v_lshl_add_u32 v6, v6, 2, s38
	v_lshl_add_u32 v9, v9, 2, s38
	v_lshl_add_u32 v8, v8, 2, s38
	ds_read_b32 v72, v3 offset:512
	ds_read_b32 v56, v2 offset:384
	ds_read_b32 v73, v5 offset:512
	ds_read_b32 v57, v4 offset:384
	ds_read_b32 v74, v7 offset:512
	ds_read_b32 v58, v6 offset:384
	ds_read_b32 v75, v9 offset:512
	ds_read_b32 v59, v8 offset:384
	v_add_u32_e32 v2, 0x43, v0
	v_med3_i32 v3, v2, s53, v235
	v_add_u32_e32 v4, 0x42, v0
	v_add_u32_e32 v6, 0x41, v0
	v_add_u32_e32 v0, 64, v0
	v_med3_i32 v2, v2, s95, v237
	v_lshl_add_u32 v3, v3, 2, s38
	v_med3_i32 v5, v4, s53, v235
	v_med3_i32 v4, v4, s95, v237
	v_med3_i32 v7, v6, s53, v235
	v_med3_i32 v6, v6, s95, v237
	v_med3_i32 v8, v0, s53, v235
	v_med3_i32 v0, v0, s95, v237
	v_lshl_add_u32 v2, v2, 2, s38
	v_lshl_add_u32 v5, v5, 2, s38
	v_lshl_add_u32 v4, v4, 2, s38
	v_lshl_add_u32 v7, v7, 2, s38
	v_lshl_add_u32 v6, v6, 2, s38
	v_lshl_add_u32 v8, v8, 2, s38
	v_lshl_add_u32 v0, v0, 2, s38
	ds_read_b32 v76, v3 offset:512
	ds_read_b32 v60, v2 offset:384
	ds_read_b32 v77, v5 offset:512
	ds_read_b32 v61, v4 offset:384
	ds_read_b32 v78, v7 offset:512
	ds_read_b32 v62, v6 offset:384
	ds_read_b32 v79, v8 offset:512
	ds_read_b32 v63, v0 offset:384
	s_mov_b64 s[16:17], 0

.LBB0_593:
	ds_read_b64_tr_b16 v[144:145], v238 offset:36864
	ds_read_b64_tr_b16 v[146:147], v238 offset:38016
	ds_read_b64_tr_b16 v[142:143], v238 offset:38080
	ds_read_b64_tr_b16 v[140:141], v238 offset:36928
	ds_read_b64_tr_b16 v[136:137], v238 offset:39168
	ds_read_b64_tr_b16 v[138:139], v238 offset:40320
	ds_read_b64_tr_b16 v[134:135], v238 offset:40384
	ds_read_b64_tr_b16 v[132:133], v238 offset:39232
	ds_read_b64_tr_b16 v[128:129], v238 offset:41472
	ds_read_b64_tr_b16 v[130:131], v238 offset:42624
	ds_read_b64_tr_b16 v[126:127], v238 offset:42688
	ds_read_b64_tr_b16 v[124:125], v238 offset:41536
	ds_read_b64_tr_b16 v[120:121], v238 offset:43776
	ds_read_b64_tr_b16 v[122:123], v238 offset:44928
	ds_read_b64_tr_b16 v[118:119], v238 offset:44992
	ds_read_b64_tr_b16 v[116:117], v238 offset:43840
	s_waitcnt lgkmcnt(0)
	s_and_b64 vcc, exec, s[4:5]
	s_cbranch_vccnz .LBB0_595
.LBB0_594:
	s_add_i32 s16, s21, s96
	s_add_i32 s16, s16, 63
	s_cmp_gt_i32 s16, s42
	s_cselect_b64 s[16:17], -1, 0
	s_and_b64 s[16:17], s[6:7], s[16:17]
	s_andn2_b64 vcc, exec, s[16:17]
	s_cbranch_vccz .Lmy_cold1
	s_waitcnt lgkmcnt(0)
	v_mov_b32_e32 v186, v180
	v_mov_b32_e32 v187, v181
	v_mov_b32_e32 v185, v189
	s_nop 0
	v_mfma_f32_32x32x16_bf16 v[64:79], v[186:189], v[80:83], 0
	v_mfma_f32_32x32x16_bf16 v[64:79], v[172:175], v[84:87], v[64:79]
	v_mfma_f32_32x32x16_bf16 v[64:79], v[160:163], v[88:91], v[64:79]
	v_mfma_f32_32x32x16_bf16 v[64:79], v[156:159], v[92:95], v[64:79]
	v_mfma_f32_32x32x16_bf16 v[64:79], v[152:155], v[96:99], v[64:79]
	v_mfma_f32_32x32x16_bf16 v[48:63], v[182:185], v[80:83], 0
	v_mfma_f32_32x32x16_bf16 v[48:63], v[176:179], v[84:87], v[48:63]
	v_mfma_f32_32x32x16_bf16 v[48:63], v[164:167], v[88:91], v[48:63]
	ds_read_b64_tr_b16 v[144:145], v238 offset:36864
	ds_read_b64_tr_b16 v[146:147], v238 offset:38016
	ds_read_b64_tr_b16 v[142:143], v238 offset:38080
	ds_read_b64_tr_b16 v[140:141], v238 offset:36928
	ds_read_b64_tr_b16 v[136:137], v238 offset:39168
	ds_read_b64_tr_b16 v[138:139], v238 offset:40320
	ds_read_b64_tr_b16 v[134:135], v238 offset:40384
	ds_read_b64_tr_b16 v[132:133], v238 offset:39232
	ds_read_b64_tr_b16 v[128:129], v238 offset:41472
	ds_read_b64_tr_b16 v[130:131], v238 offset:42624
	ds_read_b64_tr_b16 v[126:127], v238 offset:42688
	ds_read_b64_tr_b16 v[124:125], v238 offset:41536
	ds_read_b64_tr_b16 v[120:121], v238 offset:43776
	ds_read_b64_tr_b16 v[122:123], v238 offset:44928
	ds_read_b64_tr_b16 v[118:119], v238 offset:44992
	ds_read_b64_tr_b16 v[116:117], v238 offset:43840
	ds_read_b128 v[172:175], v234 offset:9216
	ds_read_b128 v[160:163], v234 offset:9248
	ds_read_b128 v[156:159], v234 offset:9280
	ds_read_b128 v[152:155], v234 offset:9312
	v_exp_f32_e32 v64, v64
	v_exp_f32_e32 v65, v65
	v_exp_f32_e32 v66, v66
	v_mfma_f32_32x32x16_bf16 v[48:63], v[168:171], v[92:95], v[48:63]
	v_exp_f32_e32 v67, v67
	v_exp_f32_e32 v68, v68
	v_exp_f32_e32 v69, v69
	v_mfma_f32_32x32x16_bf16 v[48:63], v[148:151], v[96:99], v[48:63]
	ds_read_b128 v[176:179], v234 offset:13824
	ds_read_b128 v[164:167], v234 offset:13856
	ds_read_b128 v[168:171], v234 offset:13888
	s_or_b32 s32, s32, 2
	v_exp_f32_e32 v70, v70
	v_exp_f32_e32 v71, v71
	v_exp_f32_e32 v72, v72
	v_exp_f32_e32 v73, v73
	v_exp_f32_e32 v74, v74
	v_exp_f32_e32 v75, v75
	v_exp_f32_e32 v76, v76
	v_exp_f32_e32 v77, v77
	v_exp_f32_e32 v78, v78
	v_exp_f32_e32 v79, v79
	v_cvt_pk_bf16_f32 v2, v64, v65
	v_cvt_pk_bf16_f32 v3, v66, v67
	v_cvt_pk_bf16_f32 v4, v68, v69
	v_cvt_pk_bf16_f32 v5, v70, v71
	v_cvt_pk_bf16_f32 v6, v72, v73
	v_cvt_pk_bf16_f32 v7, v74, v75
	v_cvt_pk_bf16_f32 v8, v76, v77
	v_cvt_pk_bf16_f32 v9, v78, v79
	s_waitcnt lgkmcnt(7)
	v_mfma_f32_32x32x16_bf16 v[32:47], v[2:5], v[144:147], v[32:47]
	v_exp_f32_e32 v48, v48
	v_exp_f32_e32 v49, v49
	v_exp_f32_e32 v50, v50
	v_mfma_f32_32x32x16_bf16 v[16:31], v[2:5], v[140:143], v[16:31]
	v_exp_f32_e32 v51, v51
	v_exp_f32_e32 v52, v52
	v_exp_f32_e32 v53, v53
	v_mfma_f32_32x32x16_bf16 v[32:47], v[6:9], v[136:139], v[32:47]
	v_exp_f32_e32 v54, v54
	v_exp_f32_e32 v55, v55
	v_cvt_pk_bf16_f32 v10, v48, v49
	v_cvt_pk_bf16_f32 v11, v50, v51
	v_mfma_f32_32x32x16_bf16 v[16:31], v[6:9], v[132:135], v[16:31]
	v_cvt_pk_bf16_f32 v12, v52, v53
	v_cvt_pk_bf16_f32 v13, v54, v55
	v_exp_f32_e32 v56, v56
	v_exp_f32_e32 v57, v57
	v_mfma_f32_32x32x16_bf16 v[32:47], v[10:13], v[128:131], v[32:47]
	v_exp_f32_e32 v58, v58
	v_exp_f32_e32 v59, v59
	v_exp_f32_e32 v60, v60
	v_mfma_f32_32x32x16_bf16 v[16:31], v[10:13], v[124:127], v[16:31]
	v_exp_f32_e32 v61, v61
	v_exp_f32_e32 v62, v62
	v_exp_f32_e32 v63, v63
	v_cvt_pk_bf16_f32 v148, v56, v57
	v_cvt_pk_bf16_f32 v149, v58, v59
	v_cvt_pk_bf16_f32 v150, v60, v61
	v_cvt_pk_bf16_f32 v151, v62, v63
	v_pk_add_f32 v[2:3], v[64:65], v[66:67]
	v_pk_add_f32 v[4:5], v[68:69], v[70:71]
	v_mfma_f32_32x32x16_bf16 v[32:47], v[148:151], v[120:123], v[32:47]
	v_pk_add_f32 v[6:7], v[72:73], v[74:75]
	v_pk_add_f32 v[8:9], v[76:77], v[78:79]
	v_pk_add_f32 v[10:11], v[48:49], v[50:51]
	v_pk_add_f32 v[12:13], v[52:53], v[54:55]
	v_pk_add_f32 v[14:15], v[56:57], v[58:59]
	v_pk_add_f32 v[64:65], v[60:61], v[62:63]
	v_mfma_f32_32x32x16_bf16 v[16:31], v[148:151], v[116:119], v[16:31]
	v_pk_add_f32 v[2:3], v[2:3], v[4:5]
	v_pk_add_f32 v[6:7], v[6:7], v[8:9]
	v_pk_add_f32 v[10:11], v[10:11], v[12:13]
	v_pk_add_f32 v[14:15], v[14:15], v[64:65]
	v_pk_add_f32 v[2:3], v[2:3], v[6:7]
	v_pk_add_f32 v[10:11], v[10:11], v[14:15]
	v_pk_add_f32 v[2:3], v[2:3], v[10:11]
	v_add_f32_e32 v0, v2, v3
	v_add_f32_e32 v233, v233, v0
	s_branch .LBB0_598
.Lmy_cold1:
	ds_read_b64_tr_b16 v[144:145], v238 offset:36864
	ds_read_b64_tr_b16 v[146:147], v238 offset:38016
	ds_read_b64_tr_b16 v[142:143], v238 offset:38080
	ds_read_b64_tr_b16 v[140:141], v238 offset:36928
	ds_read_b64_tr_b16 v[136:137], v238 offset:39168
	ds_read_b64_tr_b16 v[138:139], v238 offset:40320
	ds_read_b64_tr_b16 v[134:135], v238 offset:40384
	ds_read_b64_tr_b16 v[132:133], v238 offset:39232
	ds_read_b64_tr_b16 v[128:129], v238 offset:41472
	ds_read_b64_tr_b16 v[130:131], v238 offset:42624
	ds_read_b64_tr_b16 v[126:127], v238 offset:42688
	ds_read_b64_tr_b16 v[124:125], v238 offset:41536
	ds_read_b64_tr_b16 v[120:121], v238 offset:43776
	ds_read_b64_tr_b16 v[122:123], v238 offset:44928
	ds_read_b64_tr_b16 v[118:119], v238 offset:44992
	ds_read_b64_tr_b16 v[116:117], v238 offset:43840
	s_waitcnt lgkmcnt(15)
	v_mov_b32_e32 v186, v180
	v_mov_b32_e32 v187, v181
	v_mov_b32_e32 v185, v189
	s_nop 0
	v_mfma_f32_32x32x16_bf16 v[64:79], v[186:189], v[80:83], 0
	v_mfma_f32_32x32x16_bf16 v[48:63], v[182:185], v[80:83], 0

.LBB0_598:
	ds_read2_b64 v[180:183], v252 offset0:64 offset1:96
	ds_read_b128 v[148:151], v234 offset:13920
	s_andn2_b64 vcc, exec, s[14:15]
	s_cbranch_vccnz .Lmy_nowr
	s_xor_b32 s16, s97, 1
	s_mulk_i32 s16, 0x4800
	v_add_u32_e32 v0, s16, v242
	s_bitcmp0_b32 s32, 0
	s_cbranch_scc1 .Lkvb_w0
	s_waitcnt vmcnt(4)
	s_branch .Lkvb_w1

.Lmy_nowr:
	s_add_i32 s16, s41, 1
	s_cmp_lt_i32 s16, s37
	s_cselect_b64 s[16:17], -1, 0
	s_cmp_ge_i32 s41, s36
	s_cselect_b64 s[64:65], -1, 0
	s_or_b64 s[16:17], s[64:65], s[16:17]
	s_and_b64 vcc, exec, s[16:17]
	s_cbranch_vccnz .LBB0_612
	s_bitcmp1_b32 s32, 1
	s_cbranch_scc1 .Lmy_k2skip
	ds_read_b128 v[172:175], v234 offset:9216
	ds_read_b128 v[160:163], v234 offset:9248
	ds_read_b128 v[176:179], v234 offset:13824
	ds_read_b128 v[164:167], v234 offset:13856
	ds_read_b128 v[156:159], v234 offset:9280
	ds_read_b128 v[152:155], v234 offset:9312
	ds_read_b128 v[168:171], v234 offset:13888
.Lmy_k2skip:
	s_mov_b64 s[16:17], -1
	s_and_b64 vcc, exec, s[8:9]
	s_cbranch_vccz .LBB0_605
	s_add_i32 s16, s40, s63
	s_addk_i32 s16, 0xff81
	s_cmpk_gt_i32 s16, 0x7f
	s_mov_b64 s[16:17], -1
	s_cbranch_scc1 .LBB0_602
	v_add_u32_e32 v0, s40, v253
	v_add_u32_e32 v2, 27, v0
	v_med3_i32 v3, v2, s53, v235
	v_med3_i32 v2, v2, s95, v237
	v_add_u32_e32 v4, 26, v0
	v_add_u32_e32 v6, 25, v0
	v_add_u32_e32 v8, 24, v0
	v_lshl_add_u32 v3, v3, 2, s38
	v_lshl_add_u32 v2, v2, 2, s38
	v_med3_i32 v5, v4, s53, v235
	v_med3_i32 v4, v4, s95, v237
	v_med3_i32 v7, v6, s53, v235
	v_med3_i32 v6, v6, s95, v237
	v_med3_i32 v9, v8, s53, v235
	v_med3_i32 v8, v8, s95, v237
	v_lshl_add_u32 v5, v5, 2, s38
	v_lshl_add_u32 v4, v4, 2, s38
	v_lshl_add_u32 v7, v7, 2, s38
	v_lshl_add_u32 v6, v6, 2, s38
	v_lshl_add_u32 v9, v9, 2, s38
	v_lshl_add_u32 v8, v8, 2, s38
	ds_read_b32 v64, v3 offset:512
	ds_read_b32 v48, v2 offset:384
	ds_read_b32 v65, v5 offset:512
	ds_read_b32 v49, v4 offset:384
	ds_read_b32 v66, v7 offset:512
	ds_read_b32 v50, v6 offset:384
	ds_read_b32 v67, v9 offset:512
	ds_read_b32 v51, v8 offset:384
	v_add_u32_e32 v2, 19, v0
	v_med3_i32 v3, v2, s53, v235
	v_med3_i32 v2, v2, s95, v237
	v_add_u32_e32 v4, 18, v0
	v_add_u32_e32 v6, 17, v0
	v_add_u32_e32 v8, 16, v0
	v_lshl_add_u32 v3, v3, 2, s38
	v_lshl_add_u32 v2, v2, 2, s38
	v_med3_i32 v5, v4, s53, v235
	v_med3_i32 v4, v4, s95, v237
	v_med3_i32 v7, v6, s53, v235
	v_med3_i32 v6, v6, s95, v237
	v_med3_i32 v9, v8, s53, v235
	v_med3_i32 v8, v8, s95, v237
	v_lshl_add_u32 v5, v5, 2, s38
	v_lshl_add_u32 v4, v4, 2, s38
	v_lshl_add_u32 v7, v7, 2, s38
	v_lshl_add_u32 v6, v6, 2, s38
	v_lshl_add_u32 v9, v9, 2, s38
	v_lshl_add_u32 v8, v8, 2, s38
	ds_read_b32 v68, v3 offset:512
	ds_read_b32 v52, v2 offset:384
	ds_read_b32 v69, v5 offset:512
	ds_read_b32 v53, v4 offset:384
	ds_read_b32 v70, v7 offset:512
	ds_read_b32 v54, v6 offset:384
	ds_read_b32 v71, v9 offset:512
	ds_read_b32 v55, v8 offset:384
	v_add_u32_e32 v2, 11, v0
	v_med3_i32 v3, v2, s53, v235
	v_med3_i32 v2, v2, s95, v237
	v_add_u32_e32 v4, 10, v0
	v_add_u32_e32 v6, 9, v0
	v_add_u32_e32 v8, 8, v0
	v_lshl_add_u32 v3, v3, 2, s38
	v_lshl_add_u32 v2, v2, 2, s38
	v_med3_i32 v5, v4, s53, v235
	v_med3_i32 v4, v4, s95, v237
	v_med3_i32 v7, v6, s53, v235
	v_med3_i32 v6, v6, s95, v237
	v_med3_i32 v9, v8, s53, v235
	v_med3_i32 v8, v8, s95, v237
	v_lshl_add_u32 v5, v5, 2, s38
	v_lshl_add_u32 v4, v4, 2, s38
	v_lshl_add_u32 v7, v7, 2, s38
	v_lshl_add_u32 v6, v6, 2, s38
	v_lshl_add_u32 v9, v9, 2, s38
	v_lshl_add_u32 v8, v8, 2, s38
	ds_read_b32 v72, v3 offset:512
	ds_read_b32 v56, v2 offset:384
	ds_read_b32 v73, v5 offset:512
	ds_read_b32 v57, v4 offset:384
	ds_read_b32 v74, v7 offset:512
	ds_read_b32 v58, v6 offset:384
	ds_read_b32 v75, v9 offset:512
	ds_read_b32 v59, v8 offset:384
	v_add_u32_e32 v2, 3, v0
	v_med3_i32 v3, v2, s53, v235
	v_add_u32_e32 v4, 2, v0
	v_add_u32_e32 v6, 1, v0
	v_med3_i32 v2, v2, s95, v237
	v_lshl_add_u32 v3, v3, 2, s38
	v_med3_i32 v5, v4, s53, v235
	v_med3_i32 v4, v4, s95, v237
	v_med3_i32 v7, v6, s53, v235
	v_med3_i32 v6, v6, s95, v237
	v_med3_i32 v8, v0, s53, v235
	v_med3_i32 v0, v0, s95, v237
	v_lshl_add_u32 v2, v2, 2, s38
	v_lshl_add_u32 v5, v5, 2, s38
	v_lshl_add_u32 v4, v4, 2, s38
	v_lshl_add_u32 v7, v7, 2, s38
	v_lshl_add_u32 v6, v6, 2, s38
	v_lshl_add_u32 v8, v8, 2, s38
	v_lshl_add_u32 v0, v0, 2, s38
	ds_read_b32 v76, v3 offset:512
	ds_read_b32 v60, v2 offset:384
	ds_read_b32 v77, v5 offset:512
	ds_read_b32 v61, v4 offset:384
	ds_read_b32 v78, v7 offset:512
	ds_read_b32 v62, v6 offset:384
	ds_read_b32 v79, v8 offset:512
	ds_read_b32 v63, v0 offset:384
	s_mov_b64 s[16:17], 0

.LBB0_607:
	ds_read_b64_tr_b16 v[144:145], v238 offset:46080
	ds_read_b64_tr_b16 v[146:147], v238 offset:47232
	ds_read_b64_tr_b16 v[142:143], v238 offset:47296
	ds_read_b64_tr_b16 v[140:141], v238 offset:46144
	ds_read_b64_tr_b16 v[136:137], v238 offset:48384
	ds_read_b64_tr_b16 v[138:139], v238 offset:49536
	ds_read_b64_tr_b16 v[134:135], v238 offset:49600
	ds_read_b64_tr_b16 v[132:133], v238 offset:48448
	ds_read_b64_tr_b16 v[128:129], v238 offset:50688
	ds_read_b64_tr_b16 v[130:131], v238 offset:51840
	ds_read_b64_tr_b16 v[126:127], v238 offset:51904
	ds_read_b64_tr_b16 v[124:125], v238 offset:50752
	ds_read_b64_tr_b16 v[120:121], v238 offset:52992
	ds_read_b64_tr_b16 v[122:123], v238 offset:54144
	ds_read_b64_tr_b16 v[118:119], v238 offset:54208
	ds_read_b64_tr_b16 v[116:117], v238 offset:53056
	s_waitcnt lgkmcnt(0)
	s_and_b64 vcc, exec, s[4:5]
	s_cbranch_vccnz .LBB0_609
.LBB0_608:
	s_add_i32 s16, s21, s96
	s_addk_i32 s16, 0x7f
	s_cmp_gt_i32 s16, s42
	s_cselect_b64 s[16:17], -1, 0
	s_and_b64 s[16:17], s[6:7], s[16:17]
	s_andn2_b64 vcc, exec, s[16:17]
	s_cbranch_vccz .Lmy_cold2
	s_andn2_b64 vcc, exec, s[14:15]
	s_cbranch_vccnz .Lmy_t2w0
	s_waitcnt lgkmcnt(4)
	s_branch .Lmy_t2go

.Lmy_t2go:
	v_mov_b32_e32 v186, v180
	v_mov_b32_e32 v187, v181
	v_mov_b32_e32 v185, v189
	s_nop 0
	v_mfma_f32_32x32x16_bf16 v[64:79], v[186:189], v[80:83], 0
	v_mfma_f32_32x32x16_bf16 v[64:79], v[172:175], v[84:87], v[64:79]
	v_mfma_f32_32x32x16_bf16 v[64:79], v[160:163], v[88:91], v[64:79]
	v_mfma_f32_32x32x16_bf16 v[64:79], v[156:159], v[92:95], v[64:79]
	v_mfma_f32_32x32x16_bf16 v[64:79], v[152:155], v[96:99], v[64:79]
	v_mfma_f32_32x32x16_bf16 v[48:63], v[182:185], v[80:83], 0
	v_mfma_f32_32x32x16_bf16 v[48:63], v[176:179], v[84:87], v[48:63]
	v_mfma_f32_32x32x16_bf16 v[48:63], v[164:167], v[88:91], v[48:63]
	ds_read_b64_tr_b16 v[144:145], v238 offset:46080
	ds_read_b64_tr_b16 v[146:147], v238 offset:47232
	ds_read_b64_tr_b16 v[142:143], v238 offset:47296
	ds_read_b64_tr_b16 v[140:141], v238 offset:46144
	ds_read_b64_tr_b16 v[136:137], v238 offset:48384
	ds_read_b64_tr_b16 v[138:139], v238 offset:49536
	ds_read_b64_tr_b16 v[134:135], v238 offset:49600
	ds_read_b64_tr_b16 v[132:133], v238 offset:48448
	ds_read_b64_tr_b16 v[128:129], v238 offset:50688
	ds_read_b64_tr_b16 v[130:131], v238 offset:51840
	ds_read_b64_tr_b16 v[126:127], v238 offset:51904
	ds_read_b64_tr_b16 v[124:125], v238 offset:50752
	ds_read_b64_tr_b16 v[120:121], v238 offset:52992
	ds_read_b64_tr_b16 v[122:123], v238 offset:54144
	ds_read_b64_tr_b16 v[118:119], v238 offset:54208
	ds_read_b64_tr_b16 v[116:117], v238 offset:53056
	v_exp_f32_e32 v64, v64
	v_exp_f32_e32 v65, v65
	v_exp_f32_e32 v66, v66
	v_mfma_f32_32x32x16_bf16 v[48:63], v[168:171], v[92:95], v[48:63]
	v_exp_f32_e32 v67, v67
	v_exp_f32_e32 v68, v68
	v_exp_f32_e32 v69, v69
	v_mfma_f32_32x32x16_bf16 v[48:63], v[148:151], v[96:99], v[48:63]
	v_exp_f32_e32 v70, v70
	v_exp_f32_e32 v71, v71
	v_exp_f32_e32 v72, v72
	v_exp_f32_e32 v73, v73
	v_exp_f32_e32 v74, v74
	v_exp_f32_e32 v75, v75
	v_exp_f32_e32 v76, v76
	v_exp_f32_e32 v77, v77
	v_exp_f32_e32 v78, v78
	v_exp_f32_e32 v79, v79
	v_cvt_pk_bf16_f32 v2, v64, v65
	v_cvt_pk_bf16_f32 v3, v66, v67
	v_cvt_pk_bf16_f32 v4, v68, v69
	v_cvt_pk_bf16_f32 v5, v70, v71
	v_cvt_pk_bf16_f32 v6, v72, v73
	v_cvt_pk_bf16_f32 v7, v74, v75
	v_cvt_pk_bf16_f32 v8, v76, v77
	v_cvt_pk_bf16_f32 v9, v78, v79
	s_waitcnt lgkmcnt(0)
	v_mfma_f32_32x32x16_bf16 v[32:47], v[2:5], v[144:147], v[32:47]
	v_exp_f32_e32 v48, v48
	v_exp_f32_e32 v49, v49
	v_exp_f32_e32 v50, v50
	v_mfma_f32_32x32x16_bf16 v[16:31], v[2:5], v[140:143], v[16:31]
	v_exp_f32_e32 v51, v51
	v_exp_f32_e32 v52, v52
	v_exp_f32_e32 v53, v53
	v_mfma_f32_32x32x16_bf16 v[32:47], v[6:9], v[136:139], v[32:47]
	v_exp_f32_e32 v54, v54
	v_exp_f32_e32 v55, v55
	v_cvt_pk_bf16_f32 v10, v48, v49
	v_cvt_pk_bf16_f32 v11, v50, v51
	v_mfma_f32_32x32x16_bf16 v[16:31], v[6:9], v[132:135], v[16:31]
	v_cvt_pk_bf16_f32 v12, v52, v53
	v_cvt_pk_bf16_f32 v13, v54, v55
	v_exp_f32_e32 v56, v56
	v_exp_f32_e32 v57, v57
	v_mfma_f32_32x32x16_bf16 v[32:47], v[10:13], v[128:131], v[32:47]
	v_exp_f32_e32 v58, v58
	v_exp_f32_e32 v59, v59
	v_exp_f32_e32 v60, v60
	v_mfma_f32_32x32x16_bf16 v[16:31], v[10:13], v[124:127], v[16:31]
	v_exp_f32_e32 v61, v61
	v_exp_f32_e32 v62, v62
	v_exp_f32_e32 v63, v63
	v_cvt_pk_bf16_f32 v148, v56, v57
	v_cvt_pk_bf16_f32 v149, v58, v59
	v_cvt_pk_bf16_f32 v150, v60, v61
	v_cvt_pk_bf16_f32 v151, v62, v63
	v_pk_add_f32 v[2:3], v[64:65], v[66:67]
	v_pk_add_f32 v[4:5], v[68:69], v[70:71]
	v_mfma_f32_32x32x16_bf16 v[32:47], v[148:151], v[120:123], v[32:47]
	v_pk_add_f32 v[6:7], v[72:73], v[74:75]
	v_pk_add_f32 v[8:9], v[76:77], v[78:79]
	v_pk_add_f32 v[10:11], v[48:49], v[50:51]
	v_pk_add_f32 v[12:13], v[52:53], v[54:55]
	v_pk_add_f32 v[14:15], v[56:57], v[58:59]
	v_pk_add_f32 v[64:65], v[60:61], v[62:63]
	v_mfma_f32_32x32x16_bf16 v[16:31], v[148:151], v[116:119], v[16:31]
	v_pk_add_f32 v[2:3], v[2:3], v[4:5]
	v_pk_add_f32 v[6:7], v[6:7], v[8:9]
	v_pk_add_f32 v[10:11], v[10:11], v[12:13]
	v_pk_add_f32 v[14:15], v[14:15], v[64:65]
	v_pk_add_f32 v[2:3], v[2:3], v[6:7]
	v_pk_add_f32 v[10:11], v[10:11], v[14:15]
	v_pk_add_f32 v[2:3], v[2:3], v[10:11]
	v_add_f32_e32 v0, v2, v3
	v_add_f32_e32 v233, v233, v0
	s_branch .LBB0_612
.Lmy_cold2:
	ds_read_b64_tr_b16 v[144:145], v238 offset:46080
	ds_read_b64_tr_b16 v[146:147], v238 offset:47232
	ds_read_b64_tr_b16 v[142:143], v238 offset:47296
	ds_read_b64_tr_b16 v[140:141], v238 offset:46144
	ds_read_b64_tr_b16 v[136:137], v238 offset:48384
	ds_read_b64_tr_b16 v[138:139], v238 offset:49536
	ds_read_b64_tr_b16 v[134:135], v238 offset:49600
	ds_read_b64_tr_b16 v[132:133], v238 offset:48448
	ds_read_b64_tr_b16 v[128:129], v238 offset:50688
	ds_read_b64_tr_b16 v[130:131], v238 offset:51840
	ds_read_b64_tr_b16 v[126:127], v238 offset:51904
	ds_read_b64_tr_b16 v[124:125], v238 offset:50752
	ds_read_b64_tr_b16 v[120:121], v238 offset:52992
	ds_read_b64_tr_b16 v[122:123], v238 offset:54144
	ds_read_b64_tr_b16 v[118:119], v238 offset:54208
	ds_read_b64_tr_b16 v[116:117], v238 offset:53056
	s_waitcnt lgkmcnt(15)
	v_mov_b32_e32 v186, v180
	v_mov_b32_e32 v187, v181
	v_mov_b32_e32 v185, v189
	s_nop 0
	v_mfma_f32_32x32x16_bf16 v[64:79], v[186:189], v[80:83], 0
	v_mfma_f32_32x32x16_bf16 v[48:63], v[182:185], v[80:83], 0
